# also raise priority on the pv-active paths (waves with PV work but no QK work this step)
# baseline (speedup 1.0000x reference)
; __device__ __forceinline__ void finishSM(f32x16& p0, f32x16& p1, float alpha, float& l_reg, bf16x8& pa0, bf16x8& pa1, bf16x8& pa2, bf16x8& pa3) {
;     for (int r = 0; r < 16; ++r) p1[r] = __builtin_amdgcn_exp2f(p1[r]);
;     float ps = 0; for (int r = 0; r < 16; ++r) ps += p0[r]; for (int r = 0; r < 16; ++r) ps += p1[r];
;     { auto rr = __builtin_amdgcn_permlane32_swap(__float_as_uint(ps), __float_as_uint(ps), false, false);
;       ps = __uint_as_float(rr[0]) + __uint_as_float(rr[1]); }
;     l_reg = l_reg * alpha + ps;
;     ...
;     PK4(p0, 0, pa0); PK4(p0, 8, pa1); PK4(p1, 0, pa2); PK4(p1, 8, pa3);
; template <int VB, bool SK>
; __device__ __forceinline__ void pv_tile(f32x16* o, int vb0, bf16x8 pa0, bf16x8 pa1, bf16x8 pa2, bf16x8 pa3, bool act) {
;     if (SK && !act) return;
;     ...
;     PV_D0(0); PV_D0(1); PV_D0(2); PV_D0(3);
.LBB0_242:
	v_add_f32_e32 v2, 0, v189
	v_add_f32_e32 v2, v191, v2
	v_add_f32_e32 v2, v187, v2
	v_add_f32_e32 v2, v190, v2
	v_add_f32_e32 v2, v185, v2
	v_add_f32_e32 v2, v188, v2
	v_add_f32_e32 v2, v184, v2
	v_add_f32_e32 v2, v186, v2
	v_add_f32_e32 v2, v178, v2
	v_add_f32_e32 v2, v181, v2
	v_add_f32_e32 v2, v177, v2
	v_add_f32_e32 v2, v179, v2
	v_exp_f32_e32 v1, v142
	v_add_f32_e32 v2, v176, v2
	v_exp_f32_e32 v10, v143
	v_add_f32_e32 v2, v183, v2
	v_exp_f32_e32 v11, v140
	v_add_f32_e32 v2, v180, v2
	v_exp_f32_e32 v12, v141
	v_add_f32_e32 v2, v182, v2
	v_exp_f32_e32 v13, v138
	v_add_f32_e32 v2, v1, v2
	v_exp_f32_e32 v14, v139
	v_add_f32_e32 v2, v10, v2
	v_exp_f32_e32 v15, v136
	v_add_f32_e32 v2, v11, v2
	v_exp_f32_e32 v80, v137
	v_add_f32_e32 v2, v12, v2
	v_exp_f32_e32 v81, v134
	v_add_f32_e32 v2, v13, v2
	v_exp_f32_e32 v82, v135
	v_add_f32_e32 v2, v14, v2
	v_exp_f32_e32 v83, v132
	v_add_f32_e32 v2, v15, v2
	s_waitcnt vmcnt(2)
	v_exp_f32_e32 v116, v133
	v_add_f32_e32 v2, v80, v2
	v_exp_f32_e32 v117, v130
	v_add_f32_e32 v2, v81, v2
	v_exp_f32_e32 v118, v131
	v_add_f32_e32 v2, v82, v2
	v_exp_f32_e32 v119, v128
	v_add_f32_e32 v2, v83, v2
	s_waitcnt vmcnt(1)
	v_exp_f32_e32 v120, v129
	v_add_f32_e32 v2, v116, v2
	v_add_f32_e32 v2, v117, v2
	v_add_f32_e32 v2, v118, v2
	v_add_f32_e32 v2, v119, v2
	v_add_f32_e32 v232, v120, v2
	v_mov_b32_e32 v233, v232
	v_cvt_pk_bf16_f32 v2, v189, v191
	v_cvt_pk_bf16_f32 v3, v187, v190
	v_cvt_pk_bf16_f32 v4, v185, v188
	v_cvt_pk_bf16_f32 v5, v184, v186
	v_cvt_pk_bf16_f32 v6, v178, v181
	v_cvt_pk_bf16_f32 v7, v177, v179
	v_cvt_pk_bf16_f32 v8, v176, v183
	v_cvt_pk_bf16_f32 v9, v180, v182
	v_cvt_pk_bf16_f32 v10, v1, v10
	v_cvt_pk_bf16_f32 v11, v11, v12
	v_cvt_pk_bf16_f32 v12, v13, v14
	v_cvt_pk_bf16_f32 v13, v15, v80
	v_cvt_pk_bf16_f32 v80, v81, v82
	v_cvt_pk_bf16_f32 v81, v83, v116
	v_cvt_pk_bf16_f32 v82, v117, v118
	v_cvt_pk_bf16_f32 v83, v119, v120
	s_nop 1
	v_permlane32_swap_b32_e32 v232, v233
	v_permlane32_swap_b32_e32 v2, v4
	v_permlane32_swap_b32_e32 v3, v5
	v_permlane32_swap_b32_e32 v6, v8
	v_permlane32_swap_b32_e32 v7, v9
	v_permlane32_swap_b32_e32 v10, v12
	v_permlane32_swap_b32_e32 v11, v13
	v_permlane32_swap_b32_e32 v80, v82
	v_permlane32_swap_b32_e32 v81, v83
	v_add_u32_e32 v235, s60, v203
	v_add_u32_e32 v1, 0x80, v235
	v_mad_i64_i32 v[14:15], s[38:39], v1, s48, 0
	v_add_u32_e32 v1, 0xa0, v235
	v_lshlrev_b64 v[14:15], 1, v[14:15]
	v_mad_i64_i32 v[118:119], s[38:39], v1, s48, 0
	v_lshl_add_u64 v[116:117], v[204:205], 0, v[14:15]
	v_lshlrev_b64 v[118:119], 1, v[118:119]
	v_lshl_add_u64 v[14:15], v[206:207], 0, v[14:15]
	v_lshl_add_u64 v[120:121], v[204:205], 0, v[118:119]
	global_load_dwordx4 v[176:179], v[116:117], off
	global_load_dwordx4 v[180:183], v[120:121], off
	v_lshl_add_u64 v[116:117], v[206:207], 0, v[118:119]
	global_load_dwordx4 v[184:187], v[14:15], off
	global_load_dwordx4 v[188:191], v[116:117], off
	s_cmp_le_i32 s60, s55
	s_cselect_b64 s[38:39], -1, 0
	s_add_i32 s61, s60, 63
	s_cmp_ge_i32 s61, s56
	s_cselect_b64 s[62:63], -1, 0
	s_and_b64 s[38:39], s[38:39], s[62:63]
	s_andn2_b64 vcc, exec, s[38:39]
	s_cbranch_vccnz .LBB0_244
	s_setprio 1
	ds_read_b64_tr_b16 v[116:117], v215 offset:0
	ds_read_b64_tr_b16 v[118:119], v215 offset:0x800
	ds_read_b64_tr_b16 v[120:121], v215 offset:0x1000
	ds_read_b64_tr_b16 v[122:123], v215 offset:0x1800
	s_waitcnt vmcnt(4)
	ds_read_b64_tr_b16 v[124:125], v215 offset:0x2000
	ds_read_b64_tr_b16 v[126:127], v215 offset:0x2800
	ds_read_b64_tr_b16 v[128:129], v215 offset:0x3000
	ds_read_b64_tr_b16 v[130:131], v215 offset:0x3800
	s_waitcnt lgkmcnt(6)
	v_mfma_f32_32x32x16_bf16 v[64:79], v[2:5], v[116:119], v[64:79]
	ds_read_b64_tr_b16 v[116:117], v215 offset:0x200
	ds_read_b64_tr_b16 v[118:119], v215 offset:0xa00
	s_waitcnt lgkmcnt(6)
	v_mfma_f32_32x32x16_bf16 v[64:79], v[6:9], v[120:123], v[64:79]
	ds_read_b64_tr_b16 v[120:121], v215 offset:0x1200
	ds_read_b64_tr_b16 v[122:123], v215 offset:0x1a00
	s_waitcnt lgkmcnt(6)
	v_mfma_f32_32x32x16_bf16 v[64:79], v[10:13], v[124:127], v[64:79]
	ds_read_b64_tr_b16 v[124:125], v215 offset:0x2200
	ds_read_b64_tr_b16 v[126:127], v215 offset:0x2a00
	s_waitcnt lgkmcnt(6)
	v_mfma_f32_32x32x16_bf16 v[64:79], v[80:83], v[128:131], v[64:79]
	ds_read_b64_tr_b16 v[128:129], v215 offset:0x3200
	ds_read_b64_tr_b16 v[130:131], v215 offset:0x3a00
	s_waitcnt lgkmcnt(6)
	v_mfma_f32_32x32x16_bf16 v[48:63], v[2:5], v[116:119], v[48:63]
	ds_read_b64_tr_b16 v[116:117], v215 offset:0x400
	ds_read_b64_tr_b16 v[118:119], v215 offset:0xc00
	s_waitcnt lgkmcnt(6)
	v_mfma_f32_32x32x16_bf16 v[48:63], v[6:9], v[120:123], v[48:63]
	ds_read_b64_tr_b16 v[120:121], v215 offset:0x1400
	ds_read_b64_tr_b16 v[122:123], v215 offset:0x1c00
	s_waitcnt lgkmcnt(6)
	v_mfma_f32_32x32x16_bf16 v[48:63], v[10:13], v[124:127], v[48:63]
	ds_read_b64_tr_b16 v[124:125], v215 offset:0x2400
	ds_read_b64_tr_b16 v[126:127], v215 offset:0x2c00
	s_waitcnt lgkmcnt(6)
	v_mfma_f32_32x32x16_bf16 v[48:63], v[80:83], v[128:131], v[48:63]
	ds_read_b64_tr_b16 v[128:129], v215 offset:0x3400
	ds_read_b64_tr_b16 v[130:131], v215 offset:0x3c00
	s_waitcnt lgkmcnt(6)
	v_mfma_f32_32x32x16_bf16 v[32:47], v[2:5], v[116:119], v[32:47]
	ds_read_b64_tr_b16 v[116:117], v215 offset:0x600
	ds_read_b64_tr_b16 v[118:119], v215 offset:0xe00
	s_waitcnt lgkmcnt(6)
	v_mfma_f32_32x32x16_bf16 v[32:47], v[6:9], v[120:123], v[32:47]
	ds_read_b64_tr_b16 v[120:121], v215 offset:0x1600
	ds_read_b64_tr_b16 v[122:123], v215 offset:0x1e00
	s_waitcnt lgkmcnt(6)
	v_mfma_f32_32x32x16_bf16 v[32:47], v[10:13], v[124:127], v[32:47]
	ds_read_b64_tr_b16 v[124:125], v215 offset:0x2600
	ds_read_b64_tr_b16 v[126:127], v215 offset:0x2e00
	s_waitcnt lgkmcnt(6)
	v_mfma_f32_32x32x16_bf16 v[32:47], v[80:83], v[128:131], v[32:47]
	ds_read_b64_tr_b16 v[128:129], v215 offset:0x3600
	ds_read_b64_tr_b16 v[130:131], v215 offset:0x3e00
	s_waitcnt lgkmcnt(6)
	v_mfma_f32_32x32x16_bf16 v[16:31], v[2:5], v[116:119], v[16:31]
	s_waitcnt lgkmcnt(4)
	v_mfma_f32_32x32x16_bf16 v[16:31], v[6:9], v[120:123], v[16:31]
	s_waitcnt lgkmcnt(2)
	v_mfma_f32_32x32x16_bf16 v[16:31], v[10:13], v[124:127], v[16:31]
	s_waitcnt lgkmcnt(0)
	v_mfma_f32_32x32x16_bf16 v[16:31], v[80:83], v[128:131], v[16:31]

; template <int VB, bool SK>
; __device__ __forceinline__ void pv_tile(f32x16* o, int vb0, bf16x8 pa0, bf16x8 pa1, bf16x8 pa2, bf16x8 pa3, bool act) {
;     if (SK && !act) return;
;     ...
;     PV_D0(0); PV_D0(1); PV_D0(2); PV_D0(3);
.LBB0_258:
	s_setprio 1
	ds_read_b64_tr_b16 v[238:239], v215 offset:0x4000
	ds_read_b64_tr_b16 v[240:241], v215 offset:0x4800
	ds_read_b64_tr_b16 v[242:243], v215 offset:0x5000
	ds_read_b64_tr_b16 v[244:245], v215 offset:0x5800
	ds_read_b64_tr_b16 v[246:247], v215 offset:0x6000
	ds_read_b64_tr_b16 v[248:249], v215 offset:0x6800
	ds_read_b64_tr_b16 v[250:251], v215 offset:0x7000
	ds_read_b64_tr_b16 v[252:253], v215 offset:0x7800
	s_waitcnt lgkmcnt(6)
	s_nop 0
	v_mfma_f32_32x32x16_bf16 v[64:79], v[2:5], v[238:241], v[64:79]
	ds_read_b64_tr_b16 v[238:239], v215 offset:0x4200
	ds_read_b64_tr_b16 v[240:241], v215 offset:0x4a00
	s_waitcnt lgkmcnt(6)
	v_mfma_f32_32x32x16_bf16 v[64:79], v[6:9], v[242:245], v[64:79]
	ds_read_b64_tr_b16 v[242:243], v215 offset:0x5200
	ds_read_b64_tr_b16 v[244:245], v215 offset:0x5a00
	s_waitcnt lgkmcnt(6)
	v_mfma_f32_32x32x16_bf16 v[64:79], v[10:13], v[246:249], v[64:79]
	ds_read_b64_tr_b16 v[246:247], v215 offset:0x6200
	ds_read_b64_tr_b16 v[248:249], v215 offset:0x6a00
	s_waitcnt lgkmcnt(6)
	v_mfma_f32_32x32x16_bf16 v[64:79], v[192:195], v[250:253], v[64:79]
	ds_read_b64_tr_b16 v[250:251], v215 offset:0x7200
	ds_read_b64_tr_b16 v[252:253], v215 offset:0x7a00
	s_waitcnt lgkmcnt(6)
	v_mfma_f32_32x32x16_bf16 v[48:63], v[2:5], v[238:241], v[48:63]
	ds_read_b64_tr_b16 v[238:239], v215 offset:0x4400
	ds_read_b64_tr_b16 v[240:241], v215 offset:0x4c00
	s_waitcnt lgkmcnt(6)
	v_mfma_f32_32x32x16_bf16 v[48:63], v[6:9], v[242:245], v[48:63]
	ds_read_b64_tr_b16 v[242:243], v215 offset:0x5400
	ds_read_b64_tr_b16 v[244:245], v215 offset:0x5c00
	s_waitcnt lgkmcnt(6)
	v_mfma_f32_32x32x16_bf16 v[48:63], v[10:13], v[246:249], v[48:63]
	ds_read_b64_tr_b16 v[246:247], v215 offset:0x6400
	ds_read_b64_tr_b16 v[248:249], v215 offset:0x6c00
	s_waitcnt lgkmcnt(6)
	v_mfma_f32_32x32x16_bf16 v[48:63], v[192:195], v[250:253], v[48:63]
	ds_read_b64_tr_b16 v[250:251], v215 offset:0x7400
	ds_read_b64_tr_b16 v[252:253], v215 offset:0x7c00
	s_waitcnt lgkmcnt(6)
	v_mfma_f32_32x32x16_bf16 v[32:47], v[2:5], v[238:241], v[32:47]
	ds_read_b64_tr_b16 v[238:239], v215 offset:0x4600
	ds_read_b64_tr_b16 v[240:241], v215 offset:0x4e00
	s_waitcnt lgkmcnt(6)
	v_mfma_f32_32x32x16_bf16 v[32:47], v[6:9], v[242:245], v[32:47]
	ds_read_b64_tr_b16 v[242:243], v215 offset:0x5600
	ds_read_b64_tr_b16 v[244:245], v215 offset:0x5e00
	s_waitcnt lgkmcnt(6)
	v_mfma_f32_32x32x16_bf16 v[32:47], v[10:13], v[246:249], v[32:47]
	ds_read_b64_tr_b16 v[246:247], v215 offset:0x6600
	ds_read_b64_tr_b16 v[248:249], v215 offset:0x6e00
	s_waitcnt lgkmcnt(6)
	v_mfma_f32_32x32x16_bf16 v[32:47], v[192:195], v[250:253], v[32:47]
	ds_read_b64_tr_b16 v[250:251], v215 offset:0x7600
	ds_read_b64_tr_b16 v[252:253], v215 offset:0x7e00
	s_waitcnt lgkmcnt(6)
	v_mfma_f32_32x32x16_bf16 v[16:31], v[2:5], v[238:241], v[16:31]
	s_waitcnt lgkmcnt(4)
	v_mfma_f32_32x32x16_bf16 v[16:31], v[6:9], v[242:245], v[16:31]
	s_waitcnt lgkmcnt(2)
	v_mfma_f32_32x32x16_bf16 v[16:31], v[10:13], v[246:249], v[16:31]
	s_waitcnt lgkmcnt(0)
	v_mfma_f32_32x32x16_bf16 v[16:31], v[192:195], v[250:253], v[16:31]
	s_xor_b64 s[8:9], s[10:11], -1
	s_andn2_b64 vcc, exec, s[8:9]
	s_cbranch_vccnz .LBB0_261

; #define SBAR() __builtin_amdgcn_sched_barrier(0)
; #define SLOAD_HP(Kp, Vp, k0, pt) do { S.st_v0 = load8<TIn>(ROWP(Vp, k0, sr, pt)); S.st_v1 = load8<TIn>(ROWP(Vp, k0, 32 + sr, pt));              \
;                          S.st_k0 = load8<TIn>(ROWP(Kp, k0, sr, pt)); S.st_k1 = load8<TIn>(ROWP(Kp, k0, 32 + sr, pt)); } while (0)
; __device__ __forceinline__ void finishSM(f32x16& p0, f32x16& p1, float alpha, float& l_reg, bf16x8& pa0, bf16x8& pa1, bf16x8& pa2, bf16x8& pa3) {
;     for (int r = 0; r < 16; ++r) p1[r] = __builtin_amdgcn_exp2f(p1[r]);
;     float ps = 0; for (int r = 0; r < 16; ++r) ps += p0[r]; for (int r = 0; r < 16; ++r) ps += p1[r];
;     { auto rr = __builtin_amdgcn_permlane32_swap(__float_as_uint(ps), __float_as_uint(ps), false, false);
;       ps = __uint_as_float(rr[0]) + __uint_as_float(rr[1]); }
;     l_reg = l_reg * alpha + ps;
;     ...
;     PK4(p0, 0, pa0); PK4(p0, 8, pa1); PK4(p1, 0, pa2); PK4(p1, 8, pa3);
; template <class TIn, class TOut>
; __device__ __forceinline__ void causal_swa_block(const BlockRef<TIn, TOut>& cur, const BlockRef<TIn, TOut>& nxt, int skv, int W, char* lds, Seam<TIn>& S) {
;     ...
;     else { SLOAD_HP(nxt.K, nxt.V, kbn, nxt.pitch); SBAR();
; #pragma unroll
;         for (int d0 = 0; d0 < 8; ++d0) S.qr[d0] = load8<TIn>(nxt.Q + (size_t)(wid * QBLK + r32) * (size_t)nxt.pitch + d0 * 16 + hi * 8); }
;     SBAR();
;     finishSM(pA0, pA1, alA, l_reg, pa0, pa1, pa2, pa3); SBAR();
.LBB0_274:
.LBB0_275:
	s_and_b32 s8, s51, 0xffffffc0
	s_addk_i32 s8, 0xff80
	s_cmpk_gt_i32 s51, 0x80
	s_cselect_b32 s10, s8, 0
	v_add_u32_e32 v1, s10, v203
	v_mad_i64_i32 v[2:3], s[8:9], v1, s49, 0
	v_add_u32_e32 v1, s10, v217
	v_lshlrev_b64 v[2:3], 1, v[2:3]
	v_mad_i64_i32 v[6:7], s[8:9], v1, s49, 0
	v_lshl_add_u64 v[4:5], s[28:29], 0, v[2:3]
	v_lshlrev_b64 v[6:7], 1, v[6:7]
	v_lshl_add_u64 v[4:5], v[4:5], 0, v[196:197]
	v_lshl_add_u64 v[8:9], s[28:29], 0, v[6:7]
	v_lshl_add_u64 v[2:3], s[26:27], 0, v[2:3]
	v_lshl_add_u64 v[8:9], v[8:9], 0, v[196:197]
	global_load_dwordx4 v[112:115], v[4:5], off
	global_load_dwordx4 v[116:119], v[8:9], off
	v_lshl_add_u64 v[2:3], v[2:3], 0, v[196:197]
	v_lshl_add_u64 v[4:5], s[26:27], 0, v[6:7]
	v_lshl_add_u64 v[4:5], v[4:5], 0, v[196:197]
	global_load_dwordx4 v[120:123], v[2:3], off
	global_load_dwordx4 v[124:127], v[4:5], off
	v_or_b32_e32 v1, s52, v210
	v_mad_i64_i32 v[2:3], s[8:9], v1, s49, 0
	v_lshl_add_u64 v[2:3], v[2:3], 1, s[36:37]
	v_mov_b32_e32 v203, v197
	v_lshl_add_u64 v[2:3], v[2:3], 0, v[202:203]
	global_load_dwordx4 v[172:175], v[2:3], off
	global_load_dwordx4 v[168:171], v[2:3], off offset:32
	global_load_dwordx4 v[164:167], v[2:3], off offset:64
	global_load_dwordx4 v[160:163], v[2:3], off offset:96
	global_load_dwordx4 v[156:159], v[2:3], off offset:128
	global_load_dwordx4 v[152:155], v[2:3], off offset:160
	global_load_dwordx4 v[148:151], v[2:3], off offset:192
	global_load_dwordx4 v[144:147], v[2:3], off offset:224
	v_add_f32_e32 v2, 0, v189
	v_add_f32_e32 v2, v191, v2
	v_add_f32_e32 v2, v187, v2
	v_add_f32_e32 v2, v190, v2
	v_add_f32_e32 v2, v185, v2
	v_add_f32_e32 v2, v188, v2
	v_add_f32_e32 v2, v184, v2
	v_add_f32_e32 v2, v186, v2
	v_add_f32_e32 v2, v178, v2
	v_add_f32_e32 v2, v181, v2
	v_add_f32_e32 v2, v177, v2
	v_add_f32_e32 v2, v179, v2
	v_exp_f32_e32 v10, v142
	v_add_f32_e32 v2, v176, v2
	v_exp_f32_e32 v11, v143
	v_add_f32_e32 v2, v183, v2
	v_exp_f32_e32 v12, v140
	v_add_f32_e32 v2, v180, v2
	v_exp_f32_e32 v13, v141
	v_add_f32_e32 v2, v182, v2
	v_exp_f32_e32 v138, v138
	v_add_f32_e32 v2, v10, v2
	v_exp_f32_e32 v139, v139
	v_add_f32_e32 v2, v11, v2
	v_exp_f32_e32 v136, v136
	v_add_f32_e32 v2, v12, v2
	v_exp_f32_e32 v137, v137
	v_add_f32_e32 v2, v13, v2
	v_exp_f32_e32 v134, v134
	v_add_f32_e32 v2, v138, v2
	v_exp_f32_e32 v135, v135
	v_add_f32_e32 v2, v139, v2
	v_exp_f32_e32 v132, v132
	v_add_f32_e32 v2, v136, v2
	v_exp_f32_e32 v133, v133
	v_add_f32_e32 v2, v137, v2
	v_exp_f32_e32 v130, v130
	v_add_f32_e32 v2, v134, v2
	v_exp_f32_e32 v131, v131
	v_add_f32_e32 v2, v135, v2
	v_exp_f32_e32 v140, v128
	v_add_f32_e32 v2, v132, v2
	v_exp_f32_e32 v141, v129
	v_add_f32_e32 v2, v133, v2
	v_add_f32_e32 v2, v130, v2
	v_add_f32_e32 v2, v131, v2
	v_add_f32_e32 v2, v140, v2
	v_add_f32_e32 v14, v141, v2
	v_mov_b32_e32 v15, v14
	v_cvt_pk_bf16_f32 v2, v189, v191
	v_cvt_pk_bf16_f32 v3, v187, v190
	v_cvt_pk_bf16_f32 v4, v185, v188
	v_cvt_pk_bf16_f32 v5, v184, v186
	v_cvt_pk_bf16_f32 v6, v178, v181
	v_cvt_pk_bf16_f32 v7, v177, v179
	v_cvt_pk_bf16_f32 v8, v176, v183
	v_cvt_pk_bf16_f32 v9, v180, v182
	v_cvt_pk_bf16_f32 v10, v10, v11
	v_cvt_pk_bf16_f32 v11, v12, v13
	v_cvt_pk_bf16_f32 v12, v138, v139
	v_cvt_pk_bf16_f32 v13, v136, v137
	v_cvt_pk_bf16_f32 v128, v134, v135
	v_cvt_pk_bf16_f32 v129, v132, v133
	v_cvt_pk_bf16_f32 v130, v130, v131
	v_cvt_pk_bf16_f32 v131, v140, v141
	s_nop 1
	v_permlane32_swap_b32_e32 v14, v15
	v_permlane32_swap_b32_e32 v2, v4
	v_permlane32_swap_b32_e32 v3, v5
	v_permlane32_swap_b32_e32 v6, v8
	v_permlane32_swap_b32_e32 v7, v9
	v_permlane32_swap_b32_e32 v10, v12
	v_permlane32_swap_b32_e32 v11, v13
	v_permlane32_swap_b32_e32 v128, v130
	v_permlane32_swap_b32_e32 v129, v131
	s_or_b32 s8, s57, -2
	s_add_i32 s8, s8, s53
	s_lshl_b32 s10, s8, 6
	s_cmp_le_i32 s10, s55
	s_cselect_b64 s[8:9], -1, 0
	s_or_b32 s10, s10, 63
	s_cmp_ge_i32 s10, s56
	s_cselect_b64 s[10:11], -1, 0
	s_and_b64 s[8:9], s[8:9], s[10:11]
	s_andn2_b64 vcc, exec, s[8:9]
	s_cbranch_vccnz .LBB0_277
; #define ACT(t) (KBASE(t) <= qlo + QBLK - 1 && KBASE(t) + KVBLK - 1 >= qlo - W + 1)
; template <int VB, bool SK>
; __device__ __forceinline__ void pv_tile(f32x16* o, int vb0, bf16x8 pa0, bf16x8 pa1, bf16x8 pa2, bf16x8 pa3, bool act) {
;     if (SK && !act) return;
;     ...
;     PV_D0(0); PV_D0(1); PV_D0(2); PV_D0(3);
; template <class TIn, class TOut>
; __device__ __forceinline__ void causal_swa_block(const BlockRef<TIn, TOut>& cur, const BlockRef<TIn, TOut>& nxt, int skv, int W, char* lds, Seam<TIn>& S) {
;     ...
;     pv_tile<0, SK>(o, vb0, pa0, pa1, pa2, pa3, ACT(even ? NT - 2 : NT - 1));
	s_setprio 1
	ds_read_b64_tr_b16 v[132:133], v215 offset:0
	ds_read_b64_tr_b16 v[134:135], v215 offset:0x800
	ds_read_b64_tr_b16 v[136:137], v215 offset:0x1000
	ds_read_b64_tr_b16 v[138:139], v215 offset:0x1800
	ds_read_b64_tr_b16 v[140:141], v215 offset:0x2000
	ds_read_b64_tr_b16 v[142:143], v215 offset:0x2800
	ds_read_b64_tr_b16 v[176:177], v215 offset:0x3000
	ds_read_b64_tr_b16 v[178:179], v215 offset:0x3800
	s_waitcnt lgkmcnt(6)
	s_nop 0
	v_mfma_f32_32x32x16_bf16 v[64:79], v[2:5], v[132:135], v[64:79]
	ds_read_b64_tr_b16 v[132:133], v215 offset:0x200
	ds_read_b64_tr_b16 v[134:135], v215 offset:0xa00
	s_waitcnt lgkmcnt(6)
	v_mfma_f32_32x32x16_bf16 v[64:79], v[6:9], v[136:139], v[64:79]
	ds_read_b64_tr_b16 v[136:137], v215 offset:0x1200
	ds_read_b64_tr_b16 v[138:139], v215 offset:0x1a00
	s_waitcnt lgkmcnt(6)
	v_mfma_f32_32x32x16_bf16 v[64:79], v[10:13], v[140:143], v[64:79]
	ds_read_b64_tr_b16 v[140:141], v215 offset:0x2200
	ds_read_b64_tr_b16 v[142:143], v215 offset:0x2a00
	s_waitcnt lgkmcnt(6)
	v_mfma_f32_32x32x16_bf16 v[64:79], v[128:131], v[176:179], v[64:79]
	ds_read_b64_tr_b16 v[176:177], v215 offset:0x3200
	ds_read_b64_tr_b16 v[178:179], v215 offset:0x3a00
	s_waitcnt lgkmcnt(6)
	v_mfma_f32_32x32x16_bf16 v[48:63], v[2:5], v[132:135], v[48:63]
	ds_read_b64_tr_b16 v[132:133], v215 offset:0x400
	ds_read_b64_tr_b16 v[134:135], v215 offset:0xc00
	s_waitcnt lgkmcnt(6)
	v_mfma_f32_32x32x16_bf16 v[48:63], v[6:9], v[136:139], v[48:63]
	ds_read_b64_tr_b16 v[136:137], v215 offset:0x1400
	ds_read_b64_tr_b16 v[138:139], v215 offset:0x1c00
	s_waitcnt lgkmcnt(6)
	v_mfma_f32_32x32x16_bf16 v[48:63], v[10:13], v[140:143], v[48:63]
	ds_read_b64_tr_b16 v[140:141], v215 offset:0x2400
	ds_read_b64_tr_b16 v[142:143], v215 offset:0x2c00
	s_waitcnt lgkmcnt(6)
	v_mfma_f32_32x32x16_bf16 v[48:63], v[128:131], v[176:179], v[48:63]
	ds_read_b64_tr_b16 v[176:177], v215 offset:0x3400
	ds_read_b64_tr_b16 v[178:179], v215 offset:0x3c00
	s_waitcnt lgkmcnt(6)
	v_mfma_f32_32x32x16_bf16 v[32:47], v[2:5], v[132:135], v[32:47]
	ds_read_b64_tr_b16 v[132:133], v215 offset:0x600
	ds_read_b64_tr_b16 v[134:135], v215 offset:0xe00
	s_waitcnt lgkmcnt(6)
	v_mfma_f32_32x32x16_bf16 v[32:47], v[6:9], v[136:139], v[32:47]
	ds_read_b64_tr_b16 v[136:137], v215 offset:0x1600
	ds_read_b64_tr_b16 v[138:139], v215 offset:0x1e00
	s_waitcnt lgkmcnt(6)
	v_mfma_f32_32x32x16_bf16 v[32:47], v[10:13], v[140:143], v[32:47]
	ds_read_b64_tr_b16 v[140:141], v215 offset:0x2600
	ds_read_b64_tr_b16 v[142:143], v215 offset:0x2e00
	s_waitcnt lgkmcnt(6)
	v_mfma_f32_32x32x16_bf16 v[32:47], v[128:131], v[176:179], v[32:47]
	ds_read_b64_tr_b16 v[176:177], v215 offset:0x3600
	ds_read_b64_tr_b16 v[178:179], v215 offset:0x3e00
	s_waitcnt lgkmcnt(6)
	v_mfma_f32_32x32x16_bf16 v[16:31], v[2:5], v[132:135], v[16:31]
	s_waitcnt lgkmcnt(4)
	v_mfma_f32_32x32x16_bf16 v[16:31], v[6:9], v[136:139], v[16:31]
	s_waitcnt lgkmcnt(2)
	v_mfma_f32_32x32x16_bf16 v[16:31], v[10:13], v[140:143], v[16:31]
	s_waitcnt lgkmcnt(0)
	v_mfma_f32_32x32x16_bf16 v[16:31], v[128:131], v[176:179], v[16:31]

; #define SBAR() __builtin_amdgcn_sched_barrier(0)
; #define RESC(a) do { if (__any((a) < 1.f)) { if (hi == 0) al_l[r32] = (a); asm volatile("s_waitcnt lgkmcnt(0)" ::: "memory");              \
;                      for (int d_ = 0; d_ < 4; ++d_) for (int r = 0; r < 16; ++r) o[d_][r] *= al_l[crow(r, hi)]; } } while (0)
; #define ACT(t) (KBASE(t) <= qlo + QBLK - 1 && KBASE(t) + KVBLK - 1 >= qlo - W + 1)
; #define MASKT(P0_, P1_, t) do { const int kb_ = KBASE(t); if ((!SK || ACT(t)) && (kb_ + KVBLK - 1 > qlo || kb_ <= qlo + QBLK - 1 - W)) mask_tile(P0_, P1_, qm - kb_, (unsigned)W); } while (0)
; __device__ __forceinline__ void partialSM(f32x16& p0, f32x16& p1, float& m_reg, float& mn, float& alpha) {
;     ...
;     for (int r = 0; r < 16; ++r) p0[r] = fmaf(p0[r], C2, mnL); for (int r = 0; r < 16; ++r) p1[r] = fmaf(p1[r], C2, mnL);
;     for (int r = 0; r < 16; ++r) p0[r] = __builtin_amdgcn_exp2f(p0[r]);
; }
; __device__ __forceinline__ void finishSM(f32x16& p0, f32x16& p1, float alpha, float& l_reg, bf16x8& pa0, bf16x8& pa1, bf16x8& pa2, bf16x8& pa3) {
;     for (int r = 0; r < 16; ++r) p1[r] = __builtin_amdgcn_exp2f(p1[r]);
;     float ps = 0; for (int r = 0; r < 16; ++r) ps += p0[r]; for (int r = 0; r < 16; ++r) ps += p1[r];
;     { auto rr = __builtin_amdgcn_permlane32_swap(__float_as_uint(ps), __float_as_uint(ps), false, false);
;       ps = __uint_as_float(rr[0]) + __uint_as_float(rr[1]); }
;     l_reg = l_reg * alpha + ps;
;     ...
;     PK4(p0, 0, pa0); PK4(p0, 8, pa1); PK4(p1, 0, pa2); PK4(p1, 8, pa3);
; template <class TIn, class TOut>
; __device__ __forceinline__ void causal_swa_block(const BlockRef<TIn, TOut>& cur, const BlockRef<TIn, TOut>& nxt, int skv, int W, char* lds, Seam<TIn>& S) {
;     ...
;     if (even) { MASKT(pB0, pB1, NT - 1); partialSM(pB0, pB1, m_reg, mnB, alB); __syncthreads(); RESC(alB);
;         finishSM(pB0, pB1, alB, l_reg, pa0, pa1, pa2, pa3); SBAR(); pv_tile<1, SK>(o, vb0, pa0, pa1, pa2, pa3, ACT(NT - 1)); }
.LBB0_285:
	v_cndmask_b32_e64 v192, v2, v192, s[8:9]
	v_mul_f32_e32 v128, 0xbe0293ee, v192
	v_fmamk_f32 v2, v80, 0x3e0293ee, v128
	v_fmamk_f32 v3, v81, 0x3e0293ee, v128
	v_exp_f32_e32 v2, v2
	v_fmamk_f32 v4, v82, 0x3e0293ee, v128
	v_fmamk_f32 v5, v83, 0x3e0293ee, v128
	v_exp_f32_e32 v83, v3
	v_exp_f32_e32 v3, v4
	v_fmamk_f32 v6, v84, 0x3e0293ee, v128
	v_fmamk_f32 v84, v96, 0x3e0293ee, v128
	v_exp_f32_e32 v82, v5
	v_fmamk_f32 v7, v85, 0x3e0293ee, v128
	v_fmamk_f32 v9, v87, 0x3e0293ee, v128
	v_fmamk_f32 v87, v99, 0x3e0293ee, v128
	v_exp_f32_e32 v4, v6
	v_exp_f32_e32 v99, v84
	v_add_f32_e32 v84, 0, v2
	v_fmamk_f32 v8, v86, 0x3e0293ee, v128
	v_exp_f32_e32 v81, v7
	v_add_f32_e32 v84, v83, v84
	v_exp_f32_e32 v5, v8
	v_add_f32_e32 v84, v3, v84
	v_fmamk_f32 v10, v88, 0x3e0293ee, v128
	v_exp_f32_e32 v80, v9
	v_add_f32_e32 v84, v82, v84
	v_fmamk_f32 v11, v89, 0x3e0293ee, v128
	v_exp_f32_e32 v6, v10
	v_add_f32_e32 v84, v4, v84
	v_fmamk_f32 v12, v90, 0x3e0293ee, v128
	v_exp_f32_e32 v13, v11
	v_add_f32_e32 v84, v81, v84
	v_fmamk_f32 v129, v91, 0x3e0293ee, v128
	v_exp_f32_e32 v7, v12
	v_add_f32_e32 v84, v5, v84
	v_fmamk_f32 v130, v92, 0x3e0293ee, v128
	v_exp_f32_e32 v12, v129
	v_add_f32_e32 v84, v80, v84
	v_fmamk_f32 v131, v93, 0x3e0293ee, v128
	v_exp_f32_e32 v8, v130
	v_add_f32_e32 v84, v6, v84
	v_fmamk_f32 v132, v94, 0x3e0293ee, v128
	v_exp_f32_e32 v11, v131
	v_add_f32_e32 v84, v13, v84
	v_fmamk_f32 v133, v95, 0x3e0293ee, v128
	v_exp_f32_e32 v9, v132
	v_add_f32_e32 v84, v7, v84
	v_exp_f32_e32 v10, v133
	v_add_f32_e32 v84, v12, v84
	v_fmamk_f32 v85, v97, 0x3e0293ee, v128
	v_add_f32_e32 v84, v8, v84
	v_fmamk_f32 v86, v98, 0x3e0293ee, v128
	v_fmamk_f32 v88, v100, 0x3e0293ee, v128
	v_exp_f32_e32 v100, v85
	v_add_f32_e32 v84, v11, v84
	v_exp_f32_e32 v86, v86
	v_add_f32_e32 v84, v9, v84
	v_exp_f32_e32 v87, v87
	v_add_f32_e32 v84, v10, v84
	v_fmamk_f32 v89, v101, 0x3e0293ee, v128
	v_exp_f32_e32 v88, v88
	v_add_f32_e32 v84, v99, v84
	v_fmamk_f32 v90, v102, 0x3e0293ee, v128
	v_exp_f32_e32 v89, v89
	v_add_f32_e32 v84, v100, v84
	v_fmamk_f32 v91, v103, 0x3e0293ee, v128
	v_exp_f32_e32 v90, v90
	v_add_f32_e32 v84, v86, v84
	v_fmamk_f32 v92, v104, 0x3e0293ee, v128
	v_exp_f32_e32 v91, v91
	v_add_f32_e32 v84, v87, v84
	v_fmamk_f32 v93, v105, 0x3e0293ee, v128
	v_exp_f32_e32 v92, v92
	v_add_f32_e32 v84, v88, v84
	v_fmamk_f32 v94, v106, 0x3e0293ee, v128
	v_exp_f32_e32 v93, v93
	v_add_f32_e32 v84, v89, v84
	v_fmamk_f32 v95, v107, 0x3e0293ee, v128
	v_exp_f32_e32 v94, v94
	v_add_f32_e32 v84, v90, v84
	v_fmamk_f32 v96, v108, 0x3e0293ee, v128
	v_exp_f32_e32 v95, v95
	v_add_f32_e32 v84, v91, v84
	v_fmamk_f32 v97, v109, 0x3e0293ee, v128
	v_exp_f32_e32 v96, v96
	v_add_f32_e32 v84, v92, v84
	v_fmamk_f32 v98, v110, 0x3e0293ee, v128
	v_exp_f32_e32 v97, v97
	v_add_f32_e32 v84, v93, v84
	v_fmac_f32_e32 v128, 0x3e0293ee, v111
	v_exp_f32_e32 v98, v98
	v_add_f32_e32 v84, v94, v84
	v_exp_f32_e32 v101, v128
	v_add_f32_e32 v84, v95, v84
	v_add_f32_e32 v84, v96, v84
	v_add_f32_e32 v84, v97, v84
	v_add_f32_e32 v84, v98, v84
	v_add_f32_e32 v84, v101, v84
	v_mov_b32_e32 v85, v84
	v_cvt_pk_bf16_f32 v2, v2, v83
	v_cvt_pk_bf16_f32 v3, v3, v82
	v_cvt_pk_bf16_f32 v4, v4, v81
	v_cvt_pk_bf16_f32 v5, v5, v80
	v_cvt_pk_bf16_f32 v6, v6, v13
	v_cvt_pk_bf16_f32 v7, v7, v12
	v_cvt_pk_bf16_f32 v8, v8, v11
	v_cvt_pk_bf16_f32 v9, v9, v10
	v_cvt_pk_bf16_f32 v10, v99, v100
	v_cvt_pk_bf16_f32 v11, v86, v87
	v_cvt_pk_bf16_f32 v12, v88, v89
	v_cvt_pk_bf16_f32 v13, v90, v91
	v_cvt_pk_bf16_f32 v80, v92, v93
	v_cvt_pk_bf16_f32 v81, v94, v95
	v_cvt_pk_bf16_f32 v82, v96, v97
	v_cvt_pk_bf16_f32 v83, v98, v101
	s_nop 1
	v_permlane32_swap_b32_e32 v84, v85
	v_permlane32_swap_b32_e32 v2, v4
	v_permlane32_swap_b32_e32 v3, v5
	v_permlane32_swap_b32_e32 v6, v8
	v_permlane32_swap_b32_e32 v7, v9
	v_permlane32_swap_b32_e32 v10, v12
	v_permlane32_swap_b32_e32 v11, v13
	v_permlane32_swap_b32_e32 v80, v82
	v_permlane32_swap_b32_e32 v81, v83
	s_and_b64 vcc, exec, s[6:7]
	s_cbranch_vccnz .LBB0_287
	s_setprio 1
	ds_read_b64_tr_b16 v[86:87], v215 offset:0x4000
	ds_read_b64_tr_b16 v[88:89], v215 offset:0x4800
	ds_read_b64_tr_b16 v[90:91], v215 offset:0x5000
	ds_read_b64_tr_b16 v[92:93], v215 offset:0x5800
	ds_read_b64_tr_b16 v[94:95], v215 offset:0x6000
	ds_read_b64_tr_b16 v[96:97], v215 offset:0x6800
	ds_read_b64_tr_b16 v[98:99], v215 offset:0x7000
	ds_read_b64_tr_b16 v[100:101], v215 offset:0x7800
	s_waitcnt lgkmcnt(6)
	s_nop 0
	v_mfma_f32_32x32x16_bf16 v[64:79], v[2:5], v[86:89], v[64:79]
	ds_read_b64_tr_b16 v[86:87], v215 offset:0x4200
	ds_read_b64_tr_b16 v[88:89], v215 offset:0x4a00
	s_waitcnt lgkmcnt(6)
	v_mfma_f32_32x32x16_bf16 v[64:79], v[6:9], v[90:93], v[64:79]
	ds_read_b64_tr_b16 v[90:91], v215 offset:0x5200
	ds_read_b64_tr_b16 v[92:93], v215 offset:0x5a00
	s_waitcnt lgkmcnt(6)
	v_mfma_f32_32x32x16_bf16 v[64:79], v[10:13], v[94:97], v[64:79]
	ds_read_b64_tr_b16 v[94:95], v215 offset:0x6200
	ds_read_b64_tr_b16 v[96:97], v215 offset:0x6a00
	s_waitcnt lgkmcnt(6)
	v_mfma_f32_32x32x16_bf16 v[64:79], v[80:83], v[98:101], v[64:79]
	ds_read_b64_tr_b16 v[98:99], v215 offset:0x7200
	ds_read_b64_tr_b16 v[100:101], v215 offset:0x7a00
	s_waitcnt lgkmcnt(6)
	v_mfma_f32_32x32x16_bf16 v[48:63], v[2:5], v[86:89], v[48:63]
	ds_read_b64_tr_b16 v[86:87], v215 offset:0x4400
	ds_read_b64_tr_b16 v[88:89], v215 offset:0x4c00
	s_waitcnt lgkmcnt(6)
	v_mfma_f32_32x32x16_bf16 v[48:63], v[6:9], v[90:93], v[48:63]
	ds_read_b64_tr_b16 v[90:91], v215 offset:0x5400
	ds_read_b64_tr_b16 v[92:93], v215 offset:0x5c00
	s_waitcnt lgkmcnt(6)
	v_mfma_f32_32x32x16_bf16 v[48:63], v[10:13], v[94:97], v[48:63]
	ds_read_b64_tr_b16 v[94:95], v215 offset:0x6400
	ds_read_b64_tr_b16 v[96:97], v215 offset:0x6c00
	s_waitcnt lgkmcnt(6)
	v_mfma_f32_32x32x16_bf16 v[48:63], v[80:83], v[98:101], v[48:63]
	ds_read_b64_tr_b16 v[98:99], v215 offset:0x7400
	ds_read_b64_tr_b16 v[100:101], v215 offset:0x7c00
	s_waitcnt lgkmcnt(6)
	v_mfma_f32_32x32x16_bf16 v[32:47], v[2:5], v[86:89], v[32:47]
	ds_read_b64_tr_b16 v[86:87], v215 offset:0x4600
	ds_read_b64_tr_b16 v[88:89], v215 offset:0x4e00
	s_waitcnt lgkmcnt(6)
	v_mfma_f32_32x32x16_bf16 v[32:47], v[6:9], v[90:93], v[32:47]
	ds_read_b64_tr_b16 v[90:91], v215 offset:0x5600
	ds_read_b64_tr_b16 v[92:93], v215 offset:0x5e00
	s_waitcnt lgkmcnt(6)
	v_mfma_f32_32x32x16_bf16 v[32:47], v[10:13], v[94:97], v[32:47]
	ds_read_b64_tr_b16 v[94:95], v215 offset:0x6600
	ds_read_b64_tr_b16 v[96:97], v215 offset:0x6e00
	s_waitcnt lgkmcnt(6)
	v_mfma_f32_32x32x16_bf16 v[32:47], v[80:83], v[98:101], v[32:47]
	ds_read_b64_tr_b16 v[98:99], v215 offset:0x7600
	ds_read_b64_tr_b16 v[100:101], v215 offset:0x7e00
	s_waitcnt lgkmcnt(6)
	v_mfma_f32_32x32x16_bf16 v[16:31], v[2:5], v[86:89], v[16:31]
	s_waitcnt lgkmcnt(4)
	v_mfma_f32_32x32x16_bf16 v[16:31], v[6:9], v[90:93], v[16:31]
	s_waitcnt lgkmcnt(2)
	v_mfma_f32_32x32x16_bf16 v[16:31], v[10:13], v[94:97], v[16:31]
	s_waitcnt lgkmcnt(0)
	v_mfma_f32_32x32x16_bf16 v[16:31], v[80:83], v[98:101], v[16:31]
